# the one cooperative-groups grid sync (after the first phase) replaced by a relabeled copy of the kernel's own XCD-hierarchical grid barrier
# speedup vs baseline: 1.0564x; 1.0095x over previous
.LBB0_102:
	s_waitcnt lgkmcnt(0)
	global_load_dwordx4 v[22:25], v[16:17], off offset:-8
	v_add_u32_e32 v9, s4, v26
	s_mov_b64 s[12:13], 0x400
	s_addk_i32 s4, 0x2000
	v_lshl_add_u64 v[16:17], v[16:17], 0, s[12:13]
	s_mov_b64 s[12:13], 0x10000
	s_cmpk_eq_u32 s4, 0x8000
	s_waitcnt vmcnt(0)
	v_cvt_pk_bf16_f32 v50, v22, v23
	v_cvt_pk_bf16_f32 v51, v24, v25
	global_store_dwordx2 v[18:19], v[50:51], off offset:-4
	ds_read_b128 v[22:25], v9
	ds_read_b128 v[38:41], v9 offset:16
	ds_read_b128 v[42:45], v9 offset:32
	ds_read_b128 v[46:49], v9 offset:48
	v_lshlrev_b32_e32 v54, 16, v50
	v_and_b32_e32 v59, 0xffff0000, v50
	s_waitcnt lgkmcnt(3)
	v_pk_fma_f32 v[20:21], v[22:23], v[54:55], v[20:21] op_sel_hi:[1,0,1]
	v_mov_b32_e32 v60, v59
	s_waitcnt lgkmcnt(1)
	v_pk_fma_f32 v[42:43], v[42:43], v[60:61], v[20:21] op_sel_hi:[1,0,1]
	ds_read_b128 v[20:23], v9 offset:64
	v_lshlrev_b32_e32 v58, 16, v51
	v_and_b32_e32 v56, 0xffff0000, v51
	v_fmac_f32_e32 v4, v54, v54
	v_pk_mul_f32 v[50:51], v[58:59], v[58:59]
	v_pk_fma_f32 v[14:15], v[24:25], v[54:55], v[14:15] op_sel_hi:[1,0,1]
	v_add_f32_e32 v4, v4, v51
	v_pk_fma_f32 v[14:15], v[44:45], v[60:61], v[14:15] op_sel_hi:[1,0,1]
	v_add_f32_e32 v4, v50, v4
	ds_read_b128 v[50:53], v9 offset:96
	s_waitcnt lgkmcnt(1)
	v_pk_fma_f32 v[14:15], v[22:23], v[58:59], v[14:15] op_sel_hi:[1,0,1]
	ds_read_b128 v[22:25], v9 offset:80
	v_pk_fma_f32 v[20:21], v[20:21], v[58:59], v[42:43] op_sel_hi:[1,0,1]
	ds_read_b128 v[42:45], v9 offset:112
	v_pk_fma_f32 v[12:13], v[38:39], v[54:55], v[12:13] op_sel_hi:[1,0,1]
	v_pk_fma_f32 v[10:11], v[40:41], v[54:55], v[10:11] op_sel_hi:[1,0,1]
	v_pk_fma_f32 v[12:13], v[46:47], v[60:61], v[12:13] op_sel_hi:[1,0,1]
	v_pk_fma_f32 v[10:11], v[48:49], v[60:61], v[10:11] op_sel_hi:[1,0,1]
	s_waitcnt lgkmcnt(1)
	v_pk_fma_f32 v[12:13], v[22:23], v[58:59], v[12:13] op_sel_hi:[1,0,1]
	v_pk_fma_f32 v[10:11], v[24:25], v[58:59], v[10:11] op_sel_hi:[1,0,1]
	v_fmac_f32_e32 v4, v56, v56
	v_pk_fma_f32 v[20:21], v[50:51], v[56:57], v[20:21] op_sel_hi:[1,0,1]
	v_pk_fma_f32 v[14:15], v[52:53], v[56:57], v[14:15] op_sel_hi:[1,0,1]
	s_waitcnt lgkmcnt(0)
	v_pk_fma_f32 v[12:13], v[42:43], v[56:57], v[12:13] op_sel_hi:[1,0,1]
	v_pk_fma_f32 v[10:11], v[44:45], v[56:57], v[10:11] op_sel_hi:[1,0,1]
	v_lshl_add_u64 v[18:19], v[18:19], 0, s[12:13]
	s_cbranch_scc0 .LBB0_102
	v_mov_b32_dpp v16, v20 quad_perm:[1,0,3,2] row_mask:0xf bank_mask:0xf bound_ctrl:1
	v_mov_b32_dpp v17, v21 quad_perm:[1,0,3,2] row_mask:0xf bank_mask:0xf bound_ctrl:1
	v_pk_add_f32 v[16:17], v[20:21], v[16:17]
	v_mov_b32_dpp v20, v14 quad_perm:[1,0,3,2] row_mask:0xf bank_mask:0xf bound_ctrl:1
	v_mov_b32_dpp v21, v15 quad_perm:[1,0,3,2] row_mask:0xf bank_mask:0xf bound_ctrl:1
	v_pk_add_f32 v[14:15], v[14:15], v[20:21]
	v_mov_b32_dpp v18, v16 quad_perm:[2,3,0,1] row_mask:0xf bank_mask:0xf bound_ctrl:1
	v_mov_b32_dpp v19, v17 quad_perm:[2,3,0,1] row_mask:0xf bank_mask:0xf bound_ctrl:1
	v_mov_b32_dpp v20, v14 quad_perm:[2,3,0,1] row_mask:0xf bank_mask:0xf bound_ctrl:1
	v_mov_b32_dpp v21, v15 quad_perm:[2,3,0,1] row_mask:0xf bank_mask:0xf bound_ctrl:1
	v_pk_add_f32 v[16:17], v[16:17], v[18:19]
	v_pk_add_f32 v[14:15], v[14:15], v[20:21]
	v_mov_b32_dpp v24, v10 quad_perm:[1,0,3,2] row_mask:0xf bank_mask:0xf bound_ctrl:1
	v_mov_b32_dpp v18, v16 row_half_mirror row_mask:0xf bank_mask:0xf bound_ctrl:1
	v_mov_b32_dpp v19, v17 row_half_mirror row_mask:0xf bank_mask:0xf bound_ctrl:1
	v_mov_b32_dpp v20, v14 row_half_mirror row_mask:0xf bank_mask:0xf bound_ctrl:1
	v_mov_b32_dpp v21, v15 row_half_mirror row_mask:0xf bank_mask:0xf bound_ctrl:1
	v_pk_add_f32 v[16:17], v[16:17], v[18:19]
	v_pk_add_f32 v[14:15], v[14:15], v[20:21]
	v_mov_b32_dpp v25, v11 quad_perm:[1,0,3,2] row_mask:0xf bank_mask:0xf bound_ctrl:1
	v_mov_b32_dpp v18, v16 row_mirror row_mask:0xf bank_mask:0xf bound_ctrl:1
	v_mov_b32_dpp v19, v17 row_mirror row_mask:0xf bank_mask:0xf bound_ctrl:1
	v_mov_b32_dpp v20, v14 row_mirror row_mask:0xf bank_mask:0xf bound_ctrl:1
	v_mov_b32_dpp v21, v15 row_mirror row_mask:0xf bank_mask:0xf bound_ctrl:1
	v_pk_add_f32 v[16:17], v[16:17], v[18:19]
	v_pk_add_f32 v[20:21], v[14:15], v[20:21]
	ds_bpermute_b32 v18, v33, v16
	ds_bpermute_b32 v19, v33, v17
	ds_bpermute_b32 v22, v33, v20
	ds_bpermute_b32 v23, v33, v21
	v_pk_add_f32 v[10:11], v[10:11], v[24:25]
	v_add_f32_dpp v4, v4, v4 quad_perm:[1,0,3,2] row_mask:0xf bank_mask:0xf bound_ctrl:1
	s_waitcnt lgkmcnt(2)
	v_pk_add_f32 v[14:15], v[16:17], v[18:19]
	v_mov_b32_dpp v24, v10 quad_perm:[2,3,0,1] row_mask:0xf bank_mask:0xf bound_ctrl:1
	s_waitcnt lgkmcnt(0)
	v_pk_add_f32 v[18:19], v[20:21], v[22:23]
	v_mov_b32_dpp v22, v12 quad_perm:[1,0,3,2] row_mask:0xf bank_mask:0xf bound_ctrl:1
	v_mov_b32_dpp v23, v13 quad_perm:[1,0,3,2] row_mask:0xf bank_mask:0xf bound_ctrl:1
	v_pk_add_f32 v[12:13], v[12:13], v[22:23]
	v_mov_b32_dpp v25, v11 quad_perm:[2,3,0,1] row_mask:0xf bank_mask:0xf bound_ctrl:1
	v_pk_add_f32 v[10:11], v[10:11], v[24:25]
	v_mov_b32_dpp v22, v12 quad_perm:[2,3,0,1] row_mask:0xf bank_mask:0xf bound_ctrl:1
	v_mov_b32_dpp v23, v13 quad_perm:[2,3,0,1] row_mask:0xf bank_mask:0xf bound_ctrl:1
	v_pk_add_f32 v[12:13], v[12:13], v[22:23]
	v_mov_b32_dpp v24, v10 row_half_mirror row_mask:0xf bank_mask:0xf bound_ctrl:1
	v_mov_b32_dpp v25, v11 row_half_mirror row_mask:0xf bank_mask:0xf bound_ctrl:1
	v_mov_b32_dpp v22, v12 row_half_mirror row_mask:0xf bank_mask:0xf bound_ctrl:1
	v_mov_b32_dpp v23, v13 row_half_mirror row_mask:0xf bank_mask:0xf bound_ctrl:1
	v_add_f32_dpp v4, v4, v4 quad_perm:[2,3,0,1] row_mask:0xf bank_mask:0xf bound_ctrl:1
	v_pk_add_f32 v[12:13], v[12:13], v[22:23]
	v_pk_add_f32 v[10:11], v[10:11], v[24:25]
	v_add_f32_dpp v4, v4, v4 row_half_mirror row_mask:0xf bank_mask:0xf bound_ctrl:1
	v_mov_b32_dpp v22, v12 row_mirror row_mask:0xf bank_mask:0xf bound_ctrl:1
	v_mov_b32_dpp v23, v13 row_mirror row_mask:0xf bank_mask:0xf bound_ctrl:1
	v_mov_b32_dpp v24, v10 row_mirror row_mask:0xf bank_mask:0xf bound_ctrl:1
	v_mov_b32_dpp v25, v11 row_mirror row_mask:0xf bank_mask:0xf bound_ctrl:1
	v_add_f32_dpp v4, v4, v4 row_mirror row_mask:0xf bank_mask:0xf bound_ctrl:1
	v_pk_add_f32 v[12:13], v[12:13], v[22:23]
	v_pk_add_f32 v[24:25], v[10:11], v[24:25]
	ds_bpermute_b32 v9, v33, v4
	ds_bpermute_b32 v22, v33, v12
	ds_bpermute_b32 v23, v33, v13
	ds_bpermute_b32 v38, v33, v24
	ds_bpermute_b32 v39, v33, v25
	s_waitcnt lgkmcnt(4)
	v_add_f32_e32 v4, v4, v9
	ds_bpermute_b32 v9, v34, v4
	s_waitcnt lgkmcnt(3)
	v_pk_add_f32 v[10:11], v[12:13], v[22:23]
	ds_bpermute_b32 v16, v34, v14
	s_waitcnt lgkmcnt(2)
	v_pk_add_f32 v[22:23], v[24:25], v[38:39]
	ds_bpermute_b32 v17, v34, v15
	ds_bpermute_b32 v20, v34, v18
	ds_bpermute_b32 v21, v34, v19
	ds_bpermute_b32 v12, v34, v10
	ds_bpermute_b32 v13, v34, v11
	ds_bpermute_b32 v24, v34, v22
	ds_bpermute_b32 v25, v34, v23
	s_and_saveexec_b64 s[12:13], s[0:1]
	s_cbranch_execz .LBB0_92
	s_waitcnt lgkmcnt(8)
	v_add_f32_e32 v4, v4, v9
	v_fmamk_f32 v4, v4, 0x3a800000, v28
	s_mov_b32 s4, 0x800000
	v_mul_f32_e32 v9, 0x4b800000, v4
	v_cmp_gt_f32_e64 s[4:5], s4, v4
	s_waitcnt lgkmcnt(6)
	v_pk_add_f32 v[14:15], v[14:15], v[16:17]
	s_waitcnt lgkmcnt(4)
	v_pk_add_f32 v[16:17], v[18:19], v[20:21]
	v_cndmask_b32_e64 v4, v4, v9, s[4:5]
	v_rsq_f32_e32 v4, v4
	v_ashrrev_i32_e32 v9, 31, v8
	v_lshlrev_b64 v[38:39], 5, v[8:9]
	s_waitcnt lgkmcnt(2)
	v_pk_add_f32 v[10:11], v[10:11], v[12:13]
	v_mul_f32_e32 v37, 0x45800000, v4
	v_cndmask_b32_e64 v4, v4, v37, s[4:5]
	s_waitcnt lgkmcnt(0)
	v_pk_add_f32 v[12:13], v[22:23], v[24:25]
	v_lshl_add_u64 v[38:39], s[6:7], 0, v[38:39]
	v_pk_mul_f32 v[14:15], v[14:15], v[4:5] op_sel_hi:[1,0]
	v_pk_mul_f32 v[16:17], v[4:5], v[16:17] op_sel_hi:[0,1]
	v_pk_mul_f32 v[10:11], v[4:5], v[10:11] op_sel_hi:[0,1]
	v_pk_mul_f32 v[12:13], v[4:5], v[12:13] op_sel_hi:[0,1]
	v_lshl_add_u64 v[8:9], v[8:9], 2, s[90:91]
	global_store_dwordx4 v[38:39], v[14:17], off
	global_store_dwordx4 v[38:39], v[10:13], off offset:16
	global_store_dword v[8:9], v4, off
	s_branch .LBB0_92
.LBB0_105:
	v_readlane_b32 s8, v159, 0
	v_readlane_b32 s9, v159, 1
	s_waitcnt vmcnt(0)
	s_barrier
	s_mov_b64 s[2:3], exec
	v_readlane_b32 s0, v159, 2
	v_readlane_b32 s1, v159, 3
	s_and_b64 s[0:1], s[2:3], s[0:1]
	s_mov_b64 exec, s[0:1]
	s_cbranch_execz .Lxbc_215
	s_mov_b64 s[0:1], src_shared_base
	v_mov_b32_e32 v0, 0xa000
	v_mov_b32_e32 v1, s1
	s_waitcnt vmcnt(0) expcnt(0) lgkmcnt(0)
	s_getreg_b32 s0, hwreg(HW_REG_XCC_ID, 0, 4)
	flat_load_dword v2, v[0:1] sc0 sc1
	s_waitcnt vmcnt(0)
	v_mov_b32_e32 v0, 0xa004
	flat_load_dword v0, v[0:1] sc0 sc1
	s_waitcnt vmcnt(0)
	s_and_b32 s33, s0, 15
	s_waitcnt lgkmcnt(0)
	v_cmp_eq_u32_e32 vcc, 0, v2
	s_and_saveexec_b64 s[52:53], vcc
	s_cbranch_execz .Lxbc_186
	s_add_u32 s4, s8, 0x1000
	s_addc_u32 s5, s9, 0
	s_add_u32 s6, s8, 0x1100
	s_addc_u32 s7, s9, 0
	s_add_u32 s10, s8, 0x1200
	s_addc_u32 s11, s9, 0
	s_add_u32 s12, s8, 0x1300
	s_addc_u32 s13, s9, 0
	s_mov_b32 s22, 1
	s_mov_b64 s[0:1], 0
	v_mov_b64_e32 v[0:1], s[8:9]
	v_mov_b64_e32 v[2:3], s[4:5]
	v_mov_b64_e32 v[4:5], s[6:7]
	v_mov_b64_e32 v[6:7], s[10:11]
	v_mov_b64_e32 v[8:9], s[12:13]
	s_branch .Lxbc_176

.Lxbc_215:
	s_or_b64 exec, exec, s[2:3]
	s_waitcnt lgkmcnt(0)
	v_mov_b32_e32 v78, v148
	s_mov_b32 s12, s55
	s_barrier
	s_mov_b32 s13, s94
	s_cmpk_gt_i32 s12, 0x2ad1
	s_cbranch_scc1 .LBB0_171
	v_ashrrev_i32_e32 v4, 2, v78
	v_lshlrev_b32_e32 v0, 5, v4
	v_ashrrev_i32_e32 v1, 31, v0
	v_lshlrev_b32_e32 v5, 4, v78
	v_lshlrev_b64 v[0:1], 1, v[0:1]
	v_and_b32_e32 v64, 48, v5
	v_mov_b32_e32 v65, 0
	s_movk_i32 s2, 0x50
	v_lshl_add_u64 v[2:3], s[44:45], 0, v[0:1]
	v_lshl_add_u64 v[0:1], s[48:49], 0, v[0:1]
	v_mad_u64_u32 v[70:71], s[0:1], v4, s2, v[64:65]
	v_lshl_add_u64 v[66:67], v[2:3], 0, v[64:65]
	v_lshl_add_u64 v[68:69], v[0:1], 0, v[64:65]
	v_lshrrev_b32_e32 v1, 1, v78
	v_and_b32_e32 v2, 31, v78
	s_mov_b32 s0, 0xfffffc0
	v_and_b32_e32 v0, 16, v1
	v_and_or_b32 v1, v1, s0, v2
	v_and_b32_e32 v2, 0x5f, v78
	v_mad_u64_u32 v[72:73], s[0:1], v1, s2, v[0:1]
	v_mad_u32_u24 v71, v2, s2, v0
	s_mov_b32 s3, 0
	s_movk_i32 s14, 0x2000
	s_movk_i32 s15, 0x4000
	s_movk_i32 s16, 0x6000
	s_mov_b32 s17, 0x8000
	s_mov_b32 s18, 0xa000
	s_mov_b32 s19, 0xc000
	s_mov_b32 s20, 0xe000
	s_mov_b32 s21, 0x10000
	s_mov_b32 s22, 0x12000
	s_mov_b32 s23, 0x14000
	s_mov_b32 s24, 0x16000
	s_mov_b32 s25, 0x18000
	s_mov_b32 s26, 0x1a000
	s_mov_b32 s27, 0x1c000
	s_mov_b32 s28, 0x1e000
	s_mov_b32 s29, 0x20000
	s_mov_b32 s30, 0x22000
	s_mov_b32 s31, 0x24000
	s_mov_b32 s33, 0x26000
	s_mov_b32 s34, 0x28000
	s_mov_b32 s35, 0x2a000
	s_mov_b32 s52, 0x2c000
	s_mov_b32 s53, 0x2e000
	s_mov_b32 s54, 0x30000
	s_mov_b32 s55, 0x32000
	s_mov_b32 s56, 0x34000
	s_mov_b32 s57, 0x36000
	s_mov_b32 s58, 0x38000
	s_mov_b32 s59, 0x3a000
	s_mov_b32 s60, 0x3c000
	s_mov_b32 s61, 0x3e000
	s_mov_b32 s62, 0x3f000
	s_movk_i32 s63, 0x110
	s_movk_i32 s64, 0x2a00
	s_movk_i32 s65, 0xe00
	v_and_b32_e32 v161, 63, v148
	v_lshrrev_b32_e32 v162, 6, v148
	v_and_b32_e32 v163, 31, v161
	v_lshlrev_b32_e32 v163, 6, v163
	v_lshrrev_b32_e32 v164, 5, v161
	v_bfe_u32 v165, v161, 2, 2
	v_xor_b32_e32 v164, v164, v165
	v_lshl_add_u32 v163, v164, 4, v163
	v_lshrrev_b32_e32 v164, 1, v162
	v_lshl_add_u32 v154, v164, 12, v163
	v_and_b32_e32 v164, 1, v162
	v_lshl_add_u32 v156, v164, 12, v163
	v_xor_b32_e32 v155, 32, v154
	v_xor_b32_e32 v157, 32, v156
	v_lshrrev_b32_e32 v163, 2, v161
	v_lshlrev_b32_e32 v163, 6, v163
	v_and_b32_e32 v164, 3, v161
	v_bfe_u32 v165, v161, 4, 2
	v_xor_b32_e32 v164, v164, v165
	v_lshl_add_u32 v163, v164, 4, v163
	v_lshl_add_u32 v160, v162, 11, v163
	v_readfirstlane_b32 s20, v162
	s_lshl_b32 s20, s20, 11
	s_and_b32 s25, s12, 7
	s_lshr_b32 s12, s12, 3
	s_add_u32 s26, s13, 7
	s_sub_u32 s26, s26, s25
	s_lshr_b32 s26, s26, 3
	s_sub_u32 s27, 268, s25
	s_lshr_b32 s27, s27, 3
	s_mul_i32 s27, s27, 21
	s_branch .Lg1a_hdr
